# attention inner loops: 4-deep counted-lgkmcnt LDS fragment ring, V prefetch behind softmax, inline C=0 (bit-identical)
# speedup vs baseline: 1.0169x; 1.0169x over previous
; #define LAS __attribute__((address_space(3)))
; DI int crow(int i, int hh) { return (i & 3) + 8 * (i >> 2) + 4 * hh; }
; #define MFMA32(a, b, c) __builtin_amdgcn_mfma_f32_32x32x16_bf16((a), (b), (c), 0, 0, 0)
; DI void attn_item(CArgs& a, LAS unsigned char* lds, int l, int b, int h, int qb, int tid_, int wave, int lane_) {
;     ...
;         if (j + 2 < NT) attn_load(a, b, h, j + 2, F, kr, vr);
;         LAS bf16_t* Ks = (LAS bf16_t*)(lds + boff + AT_KS); LAS bf16_t* Rs = (LAS bf16_t*)(lds + boff + AT_RS); LAS bf16_t* Vs = (LAS bf16_t*)(lds + boff + AT_VS);
; #pragma unroll
;         for (int kt = 0; kt < 2; ++kt) {
;             f32x16 p = zero16();
; #pragma unroll
;             for (int ks = 0; ks < 8; ++ks) p = MFMA32(lds_b128(Ks + (32 * kt + r) * 136 + 16 * ks + 8 * hh), qf[ks], p);
; #pragma unroll
;             for (int ks = 0; ks < 4; ++ks) p = MFMA32(lds_b128(Rs + (32 * kt + r) * 72 + 16 * ks + 8 * hh), qf[8 + ks], p);
;             if (j >= 4 * qb) {
; #pragma unroll
;                 for (int i = 0; i < 16; ++i) { const int key = 64 * j + 32 * kt + crow(i, hh); if (key > qloc) p[i] = -INFINITY; } }
.LBB0_298:
	s_add_i32 s56, s0, 0
	v_add_u32_e32 v205, s56, v80
	v_add_u32_e32 v209, v205, v200
	v_add_u32_e32 v210, v205, v199
	ds_read_b128 v[212:215], v209
	ds_read_b128 v[226:229], v209 offset:32
	ds_read_b128 v[230:233], v209 offset:64
	ds_read_b128 v[238:241], v209 offset:96
	s_add_i32 s1, s4, 2
	s_cmp_ge_u32 s1, s54
	s_cbranch_scc1 .LBB0_300
	v_lshl_add_u64 v[64:65], s[44:45], 0, v[182:183]
	v_lshl_add_u64 v[66:67], s[44:45], 0, v[184:185]
	global_load_dwordx4 v[146:149], v[64:65], off
	global_load_dwordx4 v[150:153], v[66:67], off
	v_lshl_add_u64 v[64:65], s[44:45], 0, v[180:181]
	v_lshl_add_u64 v[66:67], s[44:45], 0, v[176:177]
	global_load_dwordx4 v[154:157], v[64:65], off
	global_load_dwordx4 v[158:161], v[66:67], off
	v_lshl_add_u64 v[64:65], s[44:45], 0, v[178:179]
	global_load_dwordx4 v[162:165], v[64:65], off
.LBB0_300:
	s_cmp_ge_u32 s4, s51
	s_cselect_b64 s[0:1], -1, 0
	s_cmp_lt_u32 s4, s51
	v_add_u32_e32 v208, s36, v195
	s_waitcnt lgkmcnt(3)
	v_mfma_f32_32x32x16_bf16 v[64:79], v[212:215], v[98:101], 0
	ds_read_b128 v[212:215], v209 offset:128
	s_waitcnt lgkmcnt(3)
	v_mfma_f32_32x32x16_bf16 v[64:79], v[226:229], v[102:105], v[64:79]
	ds_read_b128 v[226:229], v209 offset:160
	s_waitcnt lgkmcnt(3)
	v_mfma_f32_32x32x16_bf16 v[64:79], v[230:233], v[106:109], v[64:79]
	ds_read_b128 v[230:233], v209 offset:192
	s_waitcnt lgkmcnt(3)
	v_mfma_f32_32x32x16_bf16 v[64:79], v[238:241], v[110:113], v[64:79]
	ds_read_b128 v[238:241], v209 offset:224
	s_waitcnt lgkmcnt(3)
	v_mfma_f32_32x32x16_bf16 v[64:79], v[212:215], v[114:117], v[64:79]
	ds_read_b128 v[212:215], v210 offset:17408
	s_waitcnt lgkmcnt(3)
	v_mfma_f32_32x32x16_bf16 v[64:79], v[226:229], v[118:121], v[64:79]
	ds_read_b128 v[226:229], v210 offset:17440
	s_waitcnt lgkmcnt(3)
	v_mfma_f32_32x32x16_bf16 v[64:79], v[230:233], v[122:125], v[64:79]
	ds_read_b128 v[230:233], v210 offset:17472
	s_waitcnt lgkmcnt(3)
	v_mfma_f32_32x32x16_bf16 v[64:79], v[238:241], v[126:129], v[64:79]
	ds_read_b128 v[238:241], v210 offset:17504
	s_waitcnt lgkmcnt(3)
	v_mfma_f32_32x32x16_bf16 v[64:79], v[212:215], v[130:133], v[64:79]
	s_waitcnt lgkmcnt(2)
	v_mfma_f32_32x32x16_bf16 v[64:79], v[226:229], v[138:141], v[64:79]
	s_waitcnt lgkmcnt(1)
	v_mfma_f32_32x32x16_bf16 v[64:79], v[230:233], v[134:137], v[64:79]
	s_waitcnt lgkmcnt(0)
	v_mfma_f32_32x32x16_bf16 v[64:79], v[238:241], v[142:145], v[64:79]
	s_cbranch_scc1 .LBB0_302
	v_cmp_lt_i32_e32 vcc, v208, v174
	v_add_u32_e32 v205, 2, v208
	s_nop 8
	v_cndmask_b32_e32 v65, v223, v65, vcc
	v_cmp_le_i32_e32 vcc, v208, v174
	s_nop 1
	v_cndmask_b32_e32 v64, v223, v64, vcc
	v_cmp_le_i32_e32 vcc, v205, v174
	v_add_u32_e32 v205, 3, v208
	s_nop 0
	v_cndmask_b32_e32 v66, v223, v66, vcc
	v_cmp_le_i32_e32 vcc, v205, v174
	v_add_u32_e32 v205, 8, v208
	s_nop 0
	v_cndmask_b32_e32 v67, v223, v67, vcc
	v_cmp_le_i32_e32 vcc, v205, v174
	v_add_u32_e32 v205, 9, v208
	s_nop 0
	v_cndmask_b32_e32 v68, v223, v68, vcc
	v_cmp_le_i32_e32 vcc, v205, v174
	v_add_u32_e32 v205, 10, v208
	s_nop 0
	v_cndmask_b32_e32 v69, v223, v69, vcc
	v_cmp_le_i32_e32 vcc, v205, v174
	v_add_u32_e32 v205, 11, v208
	s_nop 0
	v_cndmask_b32_e32 v70, v223, v70, vcc
	v_cmp_le_i32_e32 vcc, v205, v174
	v_add_u32_e32 v205, 16, v208
	s_nop 0
	v_cndmask_b32_e32 v71, v223, v71, vcc
	v_cmp_le_i32_e32 vcc, v205, v174
	v_add_u32_e32 v205, 17, v208
	s_nop 0
	v_cndmask_b32_e32 v72, v223, v72, vcc
	v_cmp_le_i32_e32 vcc, v205, v174
	v_add_u32_e32 v205, 18, v208
	s_nop 0
	v_cndmask_b32_e32 v73, v223, v73, vcc
	v_cmp_le_i32_e32 vcc, v205, v174
	v_add_u32_e32 v205, 19, v208
	s_nop 0
	v_cndmask_b32_e32 v74, v223, v74, vcc
	v_cmp_le_i32_e32 vcc, v205, v174
	v_add_u32_e32 v205, 24, v208
	s_nop 0
	v_cndmask_b32_e32 v75, v223, v75, vcc
	v_cmp_le_i32_e32 vcc, v205, v174
	v_add_u32_e32 v205, 25, v208
	s_nop 0
	v_cndmask_b32_e32 v76, v223, v76, vcc
	v_cmp_le_i32_e32 vcc, v205, v174
	v_add_u32_e32 v205, 26, v208
	s_nop 0
	v_cndmask_b32_e32 v77, v223, v77, vcc
	v_cmp_le_i32_e32 vcc, v205, v174
	v_add_u32_e32 v205, 27, v208
	s_nop 0
	v_cndmask_b32_e32 v78, v223, v78, vcc
	v_cmp_le_i32_e32 vcc, v205, v174
	s_nop 1
	v_cndmask_b32_e32 v79, v223, v79, vcc

; DI float shx(float v, int o, int lane) { return __int_as_float(__builtin_amdgcn_ds_bpermute((lane ^ o) << 2, __float_as_int(v))); }
; DI int crow(int i, int hh) { return (i & 3) + 8 * (i >> 2) + 4 * hh; }
; #define MFMA32(a, b, c) __builtin_amdgcn_mfma_f32_32x32x16_bf16((a), (b), (c), 0, 0, 0)
; DI void attn_item(CArgs& a, LAS unsigned char* lds, int l, int b, int h, int qb, int tid_, int wave, int lane_) {
;     ...
;         for (int kt = 0; kt < 2; ++kt) {
;             f32x16 p = zero16();
; #pragma unroll
;             for (int ks = 0; ks < 8; ++ks) p = MFMA32(lds_b128(Ks + (32 * kt + r) * 136 + 16 * ks + 8 * hh), qf[ks], p);
; #pragma unroll
;             for (int ks = 0; ks < 4; ++ks) p = MFMA32(lds_b128(Rs + (32 * kt + r) * 72 + 16 * ks + 8 * hh), qf[8 + ks], p);
;             if (j >= 4 * qb) {
; #pragma unroll
;                 for (int i = 0; i < 16; ++i) { const int key = 64 * j + 32 * kt + crow(i, hh); if (key > qloc) p[i] = -INFINITY; } }
;             float tmax = p[0];
; #pragma unroll
;             for (int i = 1; i < 16; ++i) tmax = fmaxf(tmax, p[i]);
;             tmax = fmaxf(tmax, shx(tmax, 32, lane));
;             const float m_new = fmaxf(m_run, tmax), alpha = __builtin_amdgcn_exp2f(m_run - m_new); m_run = m_new;
;             float rsum = 0.f;
; #pragma unroll
;             for (int i = 0; i < 16; ++i) { const float e = __builtin_amdgcn_exp2f(p[i] - m_new); p[i] = e; rsum += e; }
;             l_run = l_run * alpha + rsum;
;             if (__any(alpha != 1.f)) {
;                 if (hh == 0) scr[r] = alpha;
;                 asm volatile("s_waitcnt lgkmcnt(0)" ::: "memory");
; #pragma unroll
;                 for (int i = 0; i < 16; ++i) { const float ai = scr[crow(i, hh)]; o[0][i] *= ai; o[1][i] *= ai; o[2][i] *= ai; o[3][i] *= ai; }
;             }
;             const bf16x8 pa0 = packstep<0>(p), pa1 = packstep<1>(p);
; #pragma unroll
;             for (int vt = 0; vt < 4; ++vt) {
;                 o[vt] = MFMA32(pa0, lds_b128(Vs + (32 * vt + r) * 72 + 32 * kt + 8 * hh), o[vt]);
;                 o[vt] = MFMA32(pa1, lds_b128(Vs + (32 * vt + r) * 72 + 32 * kt + 16 + 8 * hh), o[vt]); }
;         }
.LBB0_306:
	v_add3_u32 v205, s56, v199, v202
	v_add3_u32 v207, s56, v201, v202
	ds_read_b128 v[216:219], v205 offset:26624
	ds_read_b128 v[238:241], v207 offset:26624
	ds_read_b128 v[242:245], v205 offset:35840
	ds_read_b128 v[246:249], v205 offset:40448
	v_sub_f32_e32 v64, v64, v211
	v_exp_f32_e32 v212, v64
	v_sub_f32_e32 v64, v65, v211
	v_exp_f32_e32 v213, v64
	v_sub_f32_e32 v64, v66, v211
	v_exp_f32_e32 v214, v64
	v_sub_f32_e32 v64, v67, v211
	v_exp_f32_e32 v215, v64
	v_sub_f32_e32 v64, v68, v211
	v_exp_f32_e32 v225, v64
	v_sub_f32_e32 v64, v69, v211
	v_exp_f32_e32 v226, v64
	v_sub_f32_e32 v64, v70, v211
	v_exp_f32_e32 v227, v64
	v_sub_f32_e32 v64, v71, v211
	v_exp_f32_e32 v228, v64
	v_sub_f32_e32 v64, v72, v211
	v_exp_f32_e32 v229, v64
	v_sub_f32_e32 v64, v73, v211
	v_exp_f32_e32 v230, v64
	v_sub_f32_e32 v64, v74, v211
	v_exp_f32_e32 v231, v64
	v_sub_f32_e32 v64, v75, v211
	v_exp_f32_e32 v232, v64
	v_sub_f32_e32 v64, v76, v211
	v_exp_f32_e32 v233, v64
	v_sub_f32_e32 v64, v77, v211
	v_exp_f32_e32 v234, v64
	v_sub_f32_e32 v64, v78, v211
	v_exp_f32_e32 v235, v64
	v_sub_f32_e32 v72, v79, v211
	v_exp_f32_e32 v236, v72
	v_cvt_pk_bf16_f32 v64, v212, v213
	v_cvt_pk_bf16_f32 v65, v214, v215
	v_cvt_pk_bf16_f32 v66, v225, v226
	v_cvt_pk_bf16_f32 v67, v227, v228
	v_cvt_pk_bf16_f32 v72, v229, v230
	v_cvt_pk_bf16_f32 v73, v231, v232
	v_cvt_pk_bf16_f32 v74, v233, v234
	v_cvt_pk_bf16_f32 v75, v235, v236
	ds_read_b128 v[68:71], v205 offset:26656
	ds_read_b128 v[76:79], v207 offset:26656
	s_waitcnt lgkmcnt(5)
	v_mfma_f32_32x32x16_bf16 v[0:15], v[64:67], v[216:219], v[0:15]
	ds_read_b128 v[216:219], v205 offset:35872
	s_waitcnt lgkmcnt(5)
	v_mfma_f32_32x32x16_bf16 v[16:31], v[64:67], v[238:241], v[16:31]
	ds_read_b128 v[238:241], v205 offset:40480
	s_waitcnt lgkmcnt(5)
	v_mfma_f32_32x32x16_bf16 v[32:47], v[64:67], v[242:245], v[32:47]
	ds_read_b128 v[242:245], v209 offset:8704
	s_waitcnt lgkmcnt(5)
	v_mfma_f32_32x32x16_bf16 v[48:63], v[64:67], v[246:249], v[48:63]
	ds_read_b128 v[246:249], v209 offset:8736
	s_waitcnt lgkmcnt(5)
	v_mfma_f32_32x32x16_bf16 v[0:15], v[72:75], v[68:71], v[0:15]
	s_waitcnt lgkmcnt(4)
	v_mfma_f32_32x32x16_bf16 v[16:31], v[72:75], v[76:79], v[16:31]
	s_waitcnt lgkmcnt(3)
	v_mfma_f32_32x32x16_bf16 v[32:47], v[72:75], v[216:219], v[32:47]
	ds_read_b128 v[216:219], v209 offset:8768
	s_waitcnt lgkmcnt(3)
	v_mfma_f32_32x32x16_bf16 v[48:63], v[72:75], v[238:241], v[48:63]
	ds_read_b128 v[238:241], v209 offset:8800
	s_waitcnt lgkmcnt(3)
	v_mfma_f32_32x32x16_bf16 v[64:79], v[242:245], v[98:101], 0
	ds_read_b128 v[242:245], v209 offset:8832
	s_waitcnt lgkmcnt(3)
	v_mfma_f32_32x32x16_bf16 v[64:79], v[246:249], v[102:105], v[64:79]
	ds_read_b128 v[246:249], v209 offset:8864
	s_waitcnt lgkmcnt(3)
	v_mfma_f32_32x32x16_bf16 v[64:79], v[216:219], v[106:109], v[64:79]
	ds_read_b128 v[216:219], v209 offset:8896
	s_waitcnt lgkmcnt(3)
	v_mfma_f32_32x32x16_bf16 v[64:79], v[238:241], v[110:113], v[64:79]
	ds_read_b128 v[238:241], v209 offset:8928
	s_waitcnt lgkmcnt(3)
	v_mfma_f32_32x32x16_bf16 v[64:79], v[242:245], v[114:117], v[64:79]
	ds_read_b128 v[242:245], v210 offset:22016
	s_waitcnt lgkmcnt(3)
	v_mfma_f32_32x32x16_bf16 v[64:79], v[246:249], v[118:121], v[64:79]
	ds_read_b128 v[246:249], v210 offset:22048
	s_waitcnt lgkmcnt(3)
	v_mfma_f32_32x32x16_bf16 v[64:79], v[216:219], v[122:125], v[64:79]
	ds_read_b128 v[216:219], v210 offset:22080
	s_waitcnt lgkmcnt(3)
	v_mfma_f32_32x32x16_bf16 v[64:79], v[238:241], v[126:129], v[64:79]
	ds_read_b128 v[238:241], v210 offset:22112
	s_waitcnt lgkmcnt(3)
	v_mfma_f32_32x32x16_bf16 v[64:79], v[242:245], v[130:133], v[64:79]
	s_waitcnt lgkmcnt(2)
	v_mfma_f32_32x32x16_bf16 v[64:79], v[246:249], v[138:141], v[64:79]
	s_waitcnt lgkmcnt(1)
	v_mfma_f32_32x32x16_bf16 v[64:79], v[216:219], v[134:137], v[64:79]
	s_waitcnt lgkmcnt(0)
	v_mfma_f32_32x32x16_bf16 v[64:79], v[238:241], v[142:145], v[64:79]
	s_andn2_b64 vcc, exec, s[0:1]
	s_cbranch_vccnz .LBB0_308
	v_add_u32_e32 v204, 32, v208
	v_cmp_le_i32_e32 vcc, v204, v174
	v_add_u32_e32 v204, 33, v208
	s_nop 7
	v_cndmask_b32_e32 v64, v223, v64, vcc
	v_cmp_le_i32_e32 vcc, v204, v174
	v_add_u32_e32 v204, 34, v208
	s_nop 0
	v_cndmask_b32_e32 v65, v223, v65, vcc
	v_cmp_le_i32_e32 vcc, v204, v174
	v_add_u32_e32 v204, 35, v208
	s_nop 0
	v_cndmask_b32_e32 v66, v223, v66, vcc
	v_cmp_le_i32_e32 vcc, v204, v174
	v_add_u32_e32 v204, 40, v208
	s_nop 0
	v_cndmask_b32_e32 v67, v223, v67, vcc
	v_cmp_le_i32_e32 vcc, v204, v174
	v_add_u32_e32 v204, 41, v208
	s_nop 0
	v_cndmask_b32_e32 v68, v223, v68, vcc
	v_cmp_le_i32_e32 vcc, v204, v174
	v_add_u32_e32 v204, 42, v208
	s_nop 0
	v_cndmask_b32_e32 v69, v223, v69, vcc
	v_cmp_le_i32_e32 vcc, v204, v174
	v_add_u32_e32 v204, 43, v208
	s_nop 0
	v_cndmask_b32_e32 v70, v223, v70, vcc
	v_cmp_le_i32_e32 vcc, v204, v174
	v_add_u32_e32 v204, 48, v208
	s_nop 0
	v_cndmask_b32_e32 v71, v223, v71, vcc
	v_cmp_le_i32_e32 vcc, v204, v174
	v_add_u32_e32 v204, 49, v208
	s_nop 0
	v_cndmask_b32_e32 v72, v223, v72, vcc
	v_cmp_le_i32_e32 vcc, v204, v174
	v_add_u32_e32 v204, 50, v208
	s_nop 0
	v_cndmask_b32_e32 v73, v223, v73, vcc
	v_cmp_le_i32_e32 vcc, v204, v174
	v_add_u32_e32 v204, 51, v208
	s_nop 0
	v_cndmask_b32_e32 v74, v223, v74, vcc
	v_cmp_le_i32_e32 vcc, v204, v174
	v_add_u32_e32 v204, 56, v208
	s_nop 0
	v_cndmask_b32_e32 v75, v223, v75, vcc
	v_cmp_le_i32_e32 vcc, v204, v174
	v_add_u32_e32 v204, 57, v208
	s_nop 0
	v_cndmask_b32_e32 v76, v223, v76, vcc
	v_cmp_le_i32_e32 vcc, v204, v174
	v_add_u32_e32 v204, 58, v208
	s_nop 0
	v_cndmask_b32_e32 v77, v223, v77, vcc
	v_cmp_le_i32_e32 vcc, v204, v174
	v_add_u32_e32 v204, 59, v208
	s_nop 0
	v_cndmask_b32_e32 v78, v223, v78, vcc
	v_cmp_le_i32_e32 vcc, v204, v174
	s_nop 1
	v_cndmask_b32_e32 v79, v223, v79, vcc

; DI int crow(int i, int hh) { return (i & 3) + 8 * (i >> 2) + 4 * hh; }
; #define MFMA32(a, b, c) __builtin_amdgcn_mfma_f32_32x32x16_bf16((a), (b), (c), 0, 0, 0)
; DI void attn_item(CArgs& a, LAS unsigned char* lds, int l, int b, int h, int qb, int tid_, int wave, int lane_) {
;     ...
;             float rsum = 0.f;
; #pragma unroll
;             for (int i = 0; i < 16; ++i) { const float e = __builtin_amdgcn_exp2f(p[i] - m_new); p[i] = e; rsum += e; }
;             l_run = l_run * alpha + rsum;
;             if (__any(alpha != 1.f)) {
;                 if (hh == 0) scr[r] = alpha;
;                 asm volatile("s_waitcnt lgkmcnt(0)" ::: "memory");
; #pragma unroll
;                 for (int i = 0; i < 16; ++i) { const float ai = scr[crow(i, hh)]; o[0][i] *= ai; o[1][i] *= ai; o[2][i] *= ai; o[3][i] *= ai; }
;             }
;             const bf16x8 pa0 = packstep<0>(p), pa1 = packstep<1>(p);
; #pragma unroll
;             for (int vt = 0; vt < 4; ++vt) {
;                 o[vt] = MFMA32(pa0, lds_b128(Vs + (32 * vt + r) * 72 + 32 * kt + 8 * hh), o[vt]);
;                 o[vt] = MFMA32(pa1, lds_b128(Vs + (32 * vt + r) * 72 + 32 * kt + 16 + 8 * hh), o[vt]); }
;         }
;         __syncthreads();
.LBB0_312:
	ds_read_b128 v[216:219], v205 offset:26688
	ds_read_b128 v[238:241], v207 offset:26688
	ds_read_b128 v[242:245], v205 offset:35904
	ds_read_b128 v[246:249], v205 offset:40512
	v_add_f32_e32 v209, 0, v212
	v_add_f32_e32 v209, v213, v209
	v_add_f32_e32 v209, v214, v209
	v_add_f32_e32 v209, v215, v209
	v_add_f32_e32 v209, v225, v209
	v_add_f32_e32 v209, v226, v209
	v_add_f32_e32 v209, v227, v209
	v_add_f32_e32 v209, v228, v209
	v_add_f32_e32 v209, v229, v209
	v_add_f32_e32 v209, v230, v209
	v_add_f32_e32 v209, v231, v209
	v_add_f32_e32 v209, v232, v209
	v_sub_f32_e32 v64, v64, v204
	v_add_f32_e32 v209, v233, v209
	v_exp_f32_e32 v64, v64
	v_sub_f32_e32 v65, v65, v204
	v_add_f32_e32 v209, v234, v209
	v_exp_f32_e32 v65, v65
	v_sub_f32_e32 v66, v66, v204
	v_add_f32_e32 v209, v235, v209
	v_exp_f32_e32 v66, v66
	v_sub_f32_e32 v67, v67, v204
	v_add_f32_e32 v209, v236, v209
	v_exp_f32_e32 v67, v67
	v_sub_f32_e32 v68, v68, v204
	v_fmac_f32_e32 v209, v203, v206
	v_add_f32_e32 v203, 0, v64
	v_exp_f32_e32 v68, v68
	v_sub_f32_e32 v69, v69, v204
	v_add_f32_e32 v203, v65, v203
	v_exp_f32_e32 v69, v69
	v_sub_f32_e32 v70, v70, v204
	v_add_f32_e32 v203, v66, v203
	v_exp_f32_e32 v70, v70
	v_sub_f32_e32 v71, v71, v204
	v_add_f32_e32 v203, v67, v203
	v_exp_f32_e32 v71, v71
	v_sub_f32_e32 v72, v72, v204
	v_add_f32_e32 v203, v68, v203
	v_exp_f32_e32 v72, v72
	v_sub_f32_e32 v73, v73, v204
	v_add_f32_e32 v203, v69, v203
	v_exp_f32_e32 v73, v73
	v_sub_f32_e32 v74, v74, v204
	v_add_f32_e32 v203, v70, v203
	v_exp_f32_e32 v74, v74
	v_sub_f32_e32 v75, v75, v204
	v_add_f32_e32 v203, v71, v203
	v_exp_f32_e32 v75, v75
	v_sub_f32_e32 v76, v76, v204
	v_add_f32_e32 v203, v72, v203
	v_exp_f32_e32 v76, v76
	v_sub_f32_e32 v77, v77, v204
	v_add_f32_e32 v203, v73, v203
	v_exp_f32_e32 v77, v77
	v_sub_f32_e32 v78, v78, v204
	v_add_f32_e32 v203, v74, v203
	v_exp_f32_e32 v78, v78
	v_sub_f32_e32 v79, v79, v204
	v_add_f32_e32 v203, v75, v203
	v_exp_f32_e32 v79, v79
	v_add_f32_e32 v203, v76, v203
	v_add_f32_e32 v203, v77, v203
	v_add_f32_e32 v203, v78, v203
	v_cvt_pk_bf16_f32 v64, v64, v65
	v_cvt_pk_bf16_f32 v65, v66, v67
	v_cvt_pk_bf16_f32 v66, v68, v69
	v_cvt_pk_bf16_f32 v67, v70, v71
	v_add_f32_e32 v203, v79, v203
	v_cvt_pk_bf16_f32 v68, v72, v73
	v_cvt_pk_bf16_f32 v69, v74, v75
	v_cvt_pk_bf16_f32 v70, v76, v77
	v_cvt_pk_bf16_f32 v71, v78, v79
	ds_read_b128 v[72:75], v205 offset:26720
	ds_read_b128 v[76:79], v207 offset:26720
	s_waitcnt lgkmcnt(5)
	v_mfma_f32_32x32x16_bf16 v[0:15], v[64:67], v[216:219], v[0:15]
	ds_read_b128 v[216:219], v205 offset:35936
	s_add_i32 s36, s36, 64
	s_mov_b64 s[0:1], 0x2000
	v_fmac_f32_e32 v203, v209, v208
	s_waitcnt lgkmcnt(5)
	v_mfma_f32_32x32x16_bf16 v[16:31], v[64:67], v[238:241], v[16:31]
	ds_read_b128 v[238:241], v205 offset:40544
	v_lshl_add_u64 v[176:177], v[176:177], 0, s[68:69]
	v_lshl_add_u64 v[178:179], v[178:179], 0, s[68:69]
	s_waitcnt lgkmcnt(5)
	v_mfma_f32_32x32x16_bf16 v[32:47], v[64:67], v[242:245], v[32:47]
	v_lshl_add_u64 v[180:181], v[180:181], 0, s[0:1]
	v_lshl_add_u64 v[182:183], v[182:183], 0, s[58:59]
	s_waitcnt lgkmcnt(4)
	v_mfma_f32_32x32x16_bf16 v[48:63], v[64:67], v[246:249], v[48:63]
	v_lshl_add_u64 v[184:185], v[184:185], 0, s[58:59]
	s_cmp_eq_u32 s50, s36
	s_waitcnt lgkmcnt(3)
	v_mfma_f32_32x32x16_bf16 v[0:15], v[68:71], v[72:75], v[0:15]
	s_waitcnt lgkmcnt(2)
	v_mfma_f32_32x32x16_bf16 v[16:31], v[68:71], v[76:79], v[16:31]
	s_waitcnt lgkmcnt(0)
	s_barrier
	v_mfma_f32_32x32x16_bf16 v[32:47], v[68:71], v[216:219], v[32:47]
	v_mfma_f32_32x32x16_bf16 v[48:63], v[68:71], v[238:241], v[48:63]
	s_cbranch_scc1 .LBB0_314
	s_mov_b32 s4, s55
	s_branch .LBB0_296

; #define LAS __attribute__((address_space(3)))
; DI int crow(int i, int hh) { return (i & 3) + 8 * (i >> 2) + 4 * hh; }
; #define MFMA32(a, b, c) __builtin_amdgcn_mfma_f32_32x32x16_bf16((a), (b), (c), 0, 0, 0)
; DI void attn_item(CArgs& a, LAS unsigned char* lds, int l, int b, int h, int qb, int tid_, int wave, int lane_) {
;     ...
;         if (j + 2 < NT) attn_load(a, b, h, j + 2, F, kr, vr);
;         LAS bf16_t* Ks = (LAS bf16_t*)(lds + boff + AT_KS); LAS bf16_t* Rs = (LAS bf16_t*)(lds + boff + AT_RS); LAS bf16_t* Vs = (LAS bf16_t*)(lds + boff + AT_VS);
; #pragma unroll
;         for (int kt = 0; kt < 2; ++kt) {
;             f32x16 p = zero16();
; #pragma unroll
;             for (int ks = 0; ks < 8; ++ks) p = MFMA32(lds_b128(Ks + (32 * kt + r) * 136 + 16 * ks + 8 * hh), qf[ks], p);
; #pragma unroll
;             for (int ks = 0; ks < 4; ++ks) p = MFMA32(lds_b128(Rs + (32 * kt + r) * 72 + 16 * ks + 8 * hh), qf[8 + ks], p);
;             if (j >= 4 * qb) {
; #pragma unroll
;                 for (int i = 0; i < 16; ++i) { const int key = 64 * j + 32 * kt + crow(i, hh); if (key > qloc) p[i] = -INFINITY; } }
.LBB0_319:
	s_add_i32 s18, s0, 0
	v_add_u32_e32 v205, s18, v80
	v_add_u32_e32 v209, v205, v200
	v_add_u32_e32 v210, v205, v199
	ds_read_b128 v[212:215], v209
	ds_read_b128 v[226:229], v209 offset:32
	ds_read_b128 v[230:233], v209 offset:64
	ds_read_b128 v[238:241], v209 offset:96
	s_add_i32 s1, s2, 2
	s_cmp_ge_u32 s1, s47
	s_cbranch_scc1 .LBB0_321
	v_lshl_add_u64 v[64:65], s[44:45], 0, v[182:183]
	v_lshl_add_u64 v[66:67], s[44:45], 0, v[184:185]
	global_load_dwordx4 v[146:149], v[64:65], off
	global_load_dwordx4 v[150:153], v[66:67], off
	v_lshl_add_u64 v[64:65], s[44:45], 0, v[180:181]
	v_lshl_add_u64 v[66:67], s[44:45], 0, v[176:177]
	global_load_dwordx4 v[154:157], v[64:65], off
	global_load_dwordx4 v[158:161], v[66:67], off
	v_lshl_add_u64 v[64:65], s[44:45], 0, v[178:179]
	global_load_dwordx4 v[162:165], v[64:65], off
.LBB0_321:
	s_cmp_ge_u32 s2, s36
	s_cselect_b64 s[0:1], -1, 0
	s_cmp_lt_u32 s2, s36
	v_add_u32_e32 v208, s4, v195
	s_waitcnt lgkmcnt(3)
	v_mfma_f32_32x32x16_bf16 v[64:79], v[212:215], v[98:101], 0
	ds_read_b128 v[212:215], v209 offset:128
	s_waitcnt lgkmcnt(3)
	v_mfma_f32_32x32x16_bf16 v[64:79], v[226:229], v[102:105], v[64:79]
	ds_read_b128 v[226:229], v209 offset:160
	s_waitcnt lgkmcnt(3)
	v_mfma_f32_32x32x16_bf16 v[64:79], v[230:233], v[106:109], v[64:79]
	ds_read_b128 v[230:233], v209 offset:192
	s_waitcnt lgkmcnt(3)
	v_mfma_f32_32x32x16_bf16 v[64:79], v[238:241], v[110:113], v[64:79]
	ds_read_b128 v[238:241], v209 offset:224
	s_waitcnt lgkmcnt(3)
	v_mfma_f32_32x32x16_bf16 v[64:79], v[212:215], v[114:117], v[64:79]
	ds_read_b128 v[212:215], v210 offset:17408
	s_waitcnt lgkmcnt(3)
	v_mfma_f32_32x32x16_bf16 v[64:79], v[226:229], v[118:121], v[64:79]
	ds_read_b128 v[226:229], v210 offset:17440
	s_waitcnt lgkmcnt(3)
	v_mfma_f32_32x32x16_bf16 v[64:79], v[230:233], v[122:125], v[64:79]
	ds_read_b128 v[230:233], v210 offset:17472
	s_waitcnt lgkmcnt(3)
	v_mfma_f32_32x32x16_bf16 v[64:79], v[238:241], v[126:129], v[64:79]
	ds_read_b128 v[238:241], v210 offset:17504
	s_waitcnt lgkmcnt(3)
	v_mfma_f32_32x32x16_bf16 v[64:79], v[212:215], v[130:133], v[64:79]
	s_waitcnt lgkmcnt(2)
	v_mfma_f32_32x32x16_bf16 v[64:79], v[226:229], v[138:141], v[64:79]
	s_waitcnt lgkmcnt(1)
	v_mfma_f32_32x32x16_bf16 v[64:79], v[230:233], v[134:137], v[64:79]
	s_waitcnt lgkmcnt(0)
	v_mfma_f32_32x32x16_bf16 v[64:79], v[238:241], v[142:145], v[64:79]
	s_cbranch_scc1 .LBB0_323
	v_cmp_lt_i32_e32 vcc, v208, v174
	v_add_u32_e32 v205, 2, v208
	s_nop 8
	v_cndmask_b32_e32 v65, v223, v65, vcc
	v_cmp_le_i32_e32 vcc, v208, v174
	s_nop 1
	v_cndmask_b32_e32 v64, v223, v64, vcc
	v_cmp_le_i32_e32 vcc, v205, v174
	v_add_u32_e32 v205, 3, v208
	s_nop 0
	v_cndmask_b32_e32 v66, v223, v66, vcc
	v_cmp_le_i32_e32 vcc, v205, v174
	v_add_u32_e32 v205, 8, v208
	s_nop 0
	v_cndmask_b32_e32 v67, v223, v67, vcc
	v_cmp_le_i32_e32 vcc, v205, v174
	v_add_u32_e32 v205, 9, v208
	s_nop 0
	v_cndmask_b32_e32 v68, v223, v68, vcc
	v_cmp_le_i32_e32 vcc, v205, v174
	v_add_u32_e32 v205, 10, v208
	s_nop 0
	v_cndmask_b32_e32 v69, v223, v69, vcc
	v_cmp_le_i32_e32 vcc, v205, v174
	v_add_u32_e32 v205, 11, v208
	s_nop 0
	v_cndmask_b32_e32 v70, v223, v70, vcc
	v_cmp_le_i32_e32 vcc, v205, v174
	v_add_u32_e32 v205, 16, v208
	s_nop 0
	v_cndmask_b32_e32 v71, v223, v71, vcc
	v_cmp_le_i32_e32 vcc, v205, v174
	v_add_u32_e32 v205, 17, v208
	s_nop 0
	v_cndmask_b32_e32 v72, v223, v72, vcc
	v_cmp_le_i32_e32 vcc, v205, v174
	v_add_u32_e32 v205, 18, v208
	s_nop 0
	v_cndmask_b32_e32 v73, v223, v73, vcc
	v_cmp_le_i32_e32 vcc, v205, v174
	v_add_u32_e32 v205, 19, v208
	s_nop 0
	v_cndmask_b32_e32 v74, v223, v74, vcc
	v_cmp_le_i32_e32 vcc, v205, v174
	v_add_u32_e32 v205, 24, v208
	s_nop 0
	v_cndmask_b32_e32 v75, v223, v75, vcc
	v_cmp_le_i32_e32 vcc, v205, v174
	v_add_u32_e32 v205, 25, v208
	s_nop 0
	v_cndmask_b32_e32 v76, v223, v76, vcc
	v_cmp_le_i32_e32 vcc, v205, v174
	v_add_u32_e32 v205, 26, v208
	s_nop 0
	v_cndmask_b32_e32 v77, v223, v77, vcc
	v_cmp_le_i32_e32 vcc, v205, v174
	v_add_u32_e32 v205, 27, v208
	s_nop 0
	v_cndmask_b32_e32 v78, v223, v78, vcc
	v_cmp_le_i32_e32 vcc, v205, v174
	s_nop 1
	v_cndmask_b32_e32 v79, v223, v79, vcc

; DI float shx(float v, int o, int lane) { return __int_as_float(__builtin_amdgcn_ds_bpermute((lane ^ o) << 2, __float_as_int(v))); }
; DI int crow(int i, int hh) { return (i & 3) + 8 * (i >> 2) + 4 * hh; }
; #define MFMA32(a, b, c) __builtin_amdgcn_mfma_f32_32x32x16_bf16((a), (b), (c), 0, 0, 0)
; DI void attn_item(CArgs& a, LAS unsigned char* lds, int l, int b, int h, int qb, int tid_, int wave, int lane_) {
;     ...
;         for (int kt = 0; kt < 2; ++kt) {
;             f32x16 p = zero16();
; #pragma unroll
;             for (int ks = 0; ks < 8; ++ks) p = MFMA32(lds_b128(Ks + (32 * kt + r) * 136 + 16 * ks + 8 * hh), qf[ks], p);
; #pragma unroll
;             for (int ks = 0; ks < 4; ++ks) p = MFMA32(lds_b128(Rs + (32 * kt + r) * 72 + 16 * ks + 8 * hh), qf[8 + ks], p);
;             if (j >= 4 * qb) {
; #pragma unroll
;                 for (int i = 0; i < 16; ++i) { const int key = 64 * j + 32 * kt + crow(i, hh); if (key > qloc) p[i] = -INFINITY; } }
;             float tmax = p[0];
; #pragma unroll
;             for (int i = 1; i < 16; ++i) tmax = fmaxf(tmax, p[i]);
;             tmax = fmaxf(tmax, shx(tmax, 32, lane));
;             const float m_new = fmaxf(m_run, tmax), alpha = __builtin_amdgcn_exp2f(m_run - m_new); m_run = m_new;
;             float rsum = 0.f;
; #pragma unroll
;             for (int i = 0; i < 16; ++i) { const float e = __builtin_amdgcn_exp2f(p[i] - m_new); p[i] = e; rsum += e; }
;             l_run = l_run * alpha + rsum;
;             if (__any(alpha != 1.f)) {
;                 if (hh == 0) scr[r] = alpha;
;                 asm volatile("s_waitcnt lgkmcnt(0)" ::: "memory");
; #pragma unroll
;                 for (int i = 0; i < 16; ++i) { const float ai = scr[crow(i, hh)]; o[0][i] *= ai; o[1][i] *= ai; o[2][i] *= ai; o[3][i] *= ai; }
;             }
;             const bf16x8 pa0 = packstep<0>(p), pa1 = packstep<1>(p);
; #pragma unroll
;             for (int vt = 0; vt < 4; ++vt) {
;                 o[vt] = MFMA32(pa0, lds_b128(Vs + (32 * vt + r) * 72 + 32 * kt + 8 * hh), o[vt]);
;                 o[vt] = MFMA32(pa1, lds_b128(Vs + (32 * vt + r) * 72 + 32 * kt + 16 + 8 * hh), o[vt]); }
;         }
.LBB0_327:
	v_add3_u32 v205, s18, v199, v202
	v_add3_u32 v207, s18, v201, v202
	ds_read_b128 v[216:219], v205 offset:26624
	ds_read_b128 v[238:241], v207 offset:26624
	ds_read_b128 v[242:245], v205 offset:35840
	ds_read_b128 v[246:249], v205 offset:40448
	v_sub_f32_e32 v64, v64, v211
	v_exp_f32_e32 v212, v64
	v_sub_f32_e32 v64, v65, v211
	v_exp_f32_e32 v213, v64
	v_sub_f32_e32 v64, v66, v211
	v_exp_f32_e32 v214, v64
	v_sub_f32_e32 v64, v67, v211
	v_exp_f32_e32 v215, v64
	v_sub_f32_e32 v64, v68, v211
	v_exp_f32_e32 v225, v64
	v_sub_f32_e32 v64, v69, v211
	v_exp_f32_e32 v226, v64
	v_sub_f32_e32 v64, v70, v211
	v_exp_f32_e32 v227, v64
	v_sub_f32_e32 v64, v71, v211
	v_exp_f32_e32 v228, v64
	v_sub_f32_e32 v64, v72, v211
	v_exp_f32_e32 v229, v64
	v_sub_f32_e32 v64, v73, v211
	v_exp_f32_e32 v230, v64
	v_sub_f32_e32 v64, v74, v211
	v_exp_f32_e32 v231, v64
	v_sub_f32_e32 v64, v75, v211
	v_exp_f32_e32 v232, v64
	v_sub_f32_e32 v64, v76, v211
	v_exp_f32_e32 v233, v64
	v_sub_f32_e32 v64, v77, v211
	v_exp_f32_e32 v234, v64
	v_sub_f32_e32 v64, v78, v211
	v_exp_f32_e32 v235, v64
	v_sub_f32_e32 v72, v79, v211
	v_exp_f32_e32 v236, v72
	v_cvt_pk_bf16_f32 v64, v212, v213
	v_cvt_pk_bf16_f32 v65, v214, v215
	v_cvt_pk_bf16_f32 v66, v225, v226
	v_cvt_pk_bf16_f32 v67, v227, v228
	v_cvt_pk_bf16_f32 v72, v229, v230
	v_cvt_pk_bf16_f32 v73, v231, v232
	v_cvt_pk_bf16_f32 v74, v233, v234
	v_cvt_pk_bf16_f32 v75, v235, v236
	ds_read_b128 v[68:71], v205 offset:26656
	ds_read_b128 v[76:79], v207 offset:26656
	s_waitcnt lgkmcnt(5)
	v_mfma_f32_32x32x16_bf16 v[0:15], v[64:67], v[216:219], v[0:15]
	ds_read_b128 v[216:219], v205 offset:35872
	s_waitcnt lgkmcnt(5)
	v_mfma_f32_32x32x16_bf16 v[16:31], v[64:67], v[238:241], v[16:31]
	ds_read_b128 v[238:241], v205 offset:40480
	s_waitcnt lgkmcnt(5)
	v_mfma_f32_32x32x16_bf16 v[32:47], v[64:67], v[242:245], v[32:47]
	ds_read_b128 v[242:245], v209 offset:8704
	s_waitcnt lgkmcnt(5)
	v_mfma_f32_32x32x16_bf16 v[48:63], v[64:67], v[246:249], v[48:63]
	ds_read_b128 v[246:249], v209 offset:8736
	s_waitcnt lgkmcnt(5)
	v_mfma_f32_32x32x16_bf16 v[0:15], v[72:75], v[68:71], v[0:15]
	s_waitcnt lgkmcnt(4)
	v_mfma_f32_32x32x16_bf16 v[16:31], v[72:75], v[76:79], v[16:31]
	s_waitcnt lgkmcnt(3)
	v_mfma_f32_32x32x16_bf16 v[32:47], v[72:75], v[216:219], v[32:47]
	ds_read_b128 v[216:219], v209 offset:8768
	s_waitcnt lgkmcnt(3)
	v_mfma_f32_32x32x16_bf16 v[48:63], v[72:75], v[238:241], v[48:63]
	ds_read_b128 v[238:241], v209 offset:8800
	s_waitcnt lgkmcnt(3)
	v_mfma_f32_32x32x16_bf16 v[64:79], v[242:245], v[98:101], 0
	ds_read_b128 v[242:245], v209 offset:8832
	s_waitcnt lgkmcnt(3)
	v_mfma_f32_32x32x16_bf16 v[64:79], v[246:249], v[102:105], v[64:79]
	ds_read_b128 v[246:249], v209 offset:8864
	s_waitcnt lgkmcnt(3)
	v_mfma_f32_32x32x16_bf16 v[64:79], v[216:219], v[106:109], v[64:79]
	ds_read_b128 v[216:219], v209 offset:8896
	s_waitcnt lgkmcnt(3)
	v_mfma_f32_32x32x16_bf16 v[64:79], v[238:241], v[110:113], v[64:79]
	ds_read_b128 v[238:241], v209 offset:8928
	s_waitcnt lgkmcnt(3)
	v_mfma_f32_32x32x16_bf16 v[64:79], v[242:245], v[114:117], v[64:79]
	ds_read_b128 v[242:245], v210 offset:22016
	s_waitcnt lgkmcnt(3)
	v_mfma_f32_32x32x16_bf16 v[64:79], v[246:249], v[118:121], v[64:79]
	ds_read_b128 v[246:249], v210 offset:22048
	s_waitcnt lgkmcnt(3)
	v_mfma_f32_32x32x16_bf16 v[64:79], v[216:219], v[122:125], v[64:79]
	ds_read_b128 v[216:219], v210 offset:22080
	s_waitcnt lgkmcnt(3)
	v_mfma_f32_32x32x16_bf16 v[64:79], v[238:241], v[126:129], v[64:79]
	ds_read_b128 v[238:241], v210 offset:22112
	s_waitcnt lgkmcnt(3)
	v_mfma_f32_32x32x16_bf16 v[64:79], v[242:245], v[130:133], v[64:79]
	s_waitcnt lgkmcnt(2)
	v_mfma_f32_32x32x16_bf16 v[64:79], v[246:249], v[138:141], v[64:79]
	s_waitcnt lgkmcnt(1)
	v_mfma_f32_32x32x16_bf16 v[64:79], v[216:219], v[134:137], v[64:79]
	s_waitcnt lgkmcnt(0)
	v_mfma_f32_32x32x16_bf16 v[64:79], v[238:241], v[142:145], v[64:79]
	s_andn2_b64 vcc, exec, s[0:1]
	s_cbranch_vccnz .LBB0_329
	v_add_u32_e32 v204, 32, v208
	v_cmp_le_i32_e32 vcc, v204, v174
	v_add_u32_e32 v204, 33, v208
	s_nop 7
	v_cndmask_b32_e32 v64, v223, v64, vcc
	v_cmp_le_i32_e32 vcc, v204, v174
	v_add_u32_e32 v204, 34, v208
	s_nop 0
	v_cndmask_b32_e32 v65, v223, v65, vcc
	v_cmp_le_i32_e32 vcc, v204, v174
	v_add_u32_e32 v204, 35, v208
	s_nop 0
	v_cndmask_b32_e32 v66, v223, v66, vcc
	v_cmp_le_i32_e32 vcc, v204, v174
	v_add_u32_e32 v204, 40, v208
	s_nop 0
	v_cndmask_b32_e32 v67, v223, v67, vcc
	v_cmp_le_i32_e32 vcc, v204, v174
	v_add_u32_e32 v204, 41, v208
	s_nop 0
	v_cndmask_b32_e32 v68, v223, v68, vcc
	v_cmp_le_i32_e32 vcc, v204, v174
	v_add_u32_e32 v204, 42, v208
	s_nop 0
	v_cndmask_b32_e32 v69, v223, v69, vcc
	v_cmp_le_i32_e32 vcc, v204, v174
	v_add_u32_e32 v204, 43, v208
	s_nop 0
	v_cndmask_b32_e32 v70, v223, v70, vcc
	v_cmp_le_i32_e32 vcc, v204, v174
	v_add_u32_e32 v204, 48, v208
	s_nop 0
	v_cndmask_b32_e32 v71, v223, v71, vcc
	v_cmp_le_i32_e32 vcc, v204, v174
	v_add_u32_e32 v204, 49, v208
	s_nop 0
	v_cndmask_b32_e32 v72, v223, v72, vcc
	v_cmp_le_i32_e32 vcc, v204, v174
	v_add_u32_e32 v204, 50, v208
	s_nop 0
	v_cndmask_b32_e32 v73, v223, v73, vcc
	v_cmp_le_i32_e32 vcc, v204, v174
	v_add_u32_e32 v204, 51, v208
	s_nop 0
	v_cndmask_b32_e32 v74, v223, v74, vcc
	v_cmp_le_i32_e32 vcc, v204, v174
	v_add_u32_e32 v204, 56, v208
	s_nop 0
	v_cndmask_b32_e32 v75, v223, v75, vcc
	v_cmp_le_i32_e32 vcc, v204, v174
	v_add_u32_e32 v204, 57, v208
	s_nop 0
	v_cndmask_b32_e32 v76, v223, v76, vcc
	v_cmp_le_i32_e32 vcc, v204, v174
	v_add_u32_e32 v204, 58, v208
	s_nop 0
	v_cndmask_b32_e32 v77, v223, v77, vcc
	v_cmp_le_i32_e32 vcc, v204, v174
	v_add_u32_e32 v204, 59, v208
	s_nop 0
	v_cndmask_b32_e32 v78, v223, v78, vcc
	v_cmp_le_i32_e32 vcc, v204, v174
	s_nop 1
	v_cndmask_b32_e32 v79, v223, v79, vcc

; DI int crow(int i, int hh) { return (i & 3) + 8 * (i >> 2) + 4 * hh; }
; #define MFMA32(a, b, c) __builtin_amdgcn_mfma_f32_32x32x16_bf16((a), (b), (c), 0, 0, 0)
; DI void attn_item(CArgs& a, LAS unsigned char* lds, int l, int b, int h, int qb, int tid_, int wave, int lane_) {
;     ...
;             float rsum = 0.f;
; #pragma unroll
;             for (int i = 0; i < 16; ++i) { const float e = __builtin_amdgcn_exp2f(p[i] - m_new); p[i] = e; rsum += e; }
;             l_run = l_run * alpha + rsum;
;             if (__any(alpha != 1.f)) {
;                 if (hh == 0) scr[r] = alpha;
;                 asm volatile("s_waitcnt lgkmcnt(0)" ::: "memory");
; #pragma unroll
;                 for (int i = 0; i < 16; ++i) { const float ai = scr[crow(i, hh)]; o[0][i] *= ai; o[1][i] *= ai; o[2][i] *= ai; o[3][i] *= ai; }
;             }
;             const bf16x8 pa0 = packstep<0>(p), pa1 = packstep<1>(p);
; #pragma unroll
;             for (int vt = 0; vt < 4; ++vt) {
;                 o[vt] = MFMA32(pa0, lds_b128(Vs + (32 * vt + r) * 72 + 32 * kt + 8 * hh), o[vt]);
;                 o[vt] = MFMA32(pa1, lds_b128(Vs + (32 * vt + r) * 72 + 32 * kt + 16 + 8 * hh), o[vt]); }
;         }
;         __syncthreads();
.LBB0_333:
	ds_read_b128 v[216:219], v205 offset:26688
	ds_read_b128 v[238:241], v207 offset:26688
	ds_read_b128 v[242:245], v205 offset:35904
	ds_read_b128 v[246:249], v205 offset:40512
	v_add_f32_e32 v209, 0, v212
	v_add_f32_e32 v209, v213, v209
	v_add_f32_e32 v209, v214, v209
	v_add_f32_e32 v209, v215, v209
	v_add_f32_e32 v209, v225, v209
	v_add_f32_e32 v209, v226, v209
	v_add_f32_e32 v209, v227, v209
	v_add_f32_e32 v209, v228, v209
	v_add_f32_e32 v209, v229, v209
	v_add_f32_e32 v209, v230, v209
	v_add_f32_e32 v209, v231, v209
	v_add_f32_e32 v209, v232, v209
	v_sub_f32_e32 v64, v64, v204
	v_add_f32_e32 v209, v233, v209
	v_exp_f32_e32 v64, v64
	v_sub_f32_e32 v65, v65, v204
	v_add_f32_e32 v209, v234, v209
	v_exp_f32_e32 v65, v65
	v_sub_f32_e32 v66, v66, v204
	v_add_f32_e32 v209, v235, v209
	v_exp_f32_e32 v66, v66
	v_sub_f32_e32 v67, v67, v204
	v_add_f32_e32 v209, v236, v209
	v_exp_f32_e32 v67, v67
	v_sub_f32_e32 v68, v68, v204
	v_fmac_f32_e32 v209, v203, v206
	v_add_f32_e32 v203, 0, v64
	v_exp_f32_e32 v68, v68
	v_sub_f32_e32 v69, v69, v204
	v_add_f32_e32 v203, v65, v203
	v_exp_f32_e32 v69, v69
	v_sub_f32_e32 v70, v70, v204
	v_add_f32_e32 v203, v66, v203
	v_exp_f32_e32 v70, v70
	v_sub_f32_e32 v71, v71, v204
	v_add_f32_e32 v203, v67, v203
	v_exp_f32_e32 v71, v71
	v_sub_f32_e32 v72, v72, v204
	v_add_f32_e32 v203, v68, v203
	v_exp_f32_e32 v72, v72
	v_sub_f32_e32 v73, v73, v204
	v_add_f32_e32 v203, v69, v203
	v_exp_f32_e32 v73, v73
	v_sub_f32_e32 v74, v74, v204
	v_add_f32_e32 v203, v70, v203
	v_exp_f32_e32 v74, v74
	v_sub_f32_e32 v75, v75, v204
	v_add_f32_e32 v203, v71, v203
	v_exp_f32_e32 v75, v75
	v_sub_f32_e32 v76, v76, v204
	v_add_f32_e32 v203, v72, v203
	v_exp_f32_e32 v76, v76
	v_sub_f32_e32 v77, v77, v204
	v_add_f32_e32 v203, v73, v203
	v_exp_f32_e32 v77, v77
	v_sub_f32_e32 v78, v78, v204
	v_add_f32_e32 v203, v74, v203
	v_exp_f32_e32 v78, v78
	v_sub_f32_e32 v79, v79, v204
	v_add_f32_e32 v203, v75, v203
	v_exp_f32_e32 v79, v79
	v_add_f32_e32 v203, v76, v203
	v_add_f32_e32 v203, v77, v203
	v_add_f32_e32 v203, v78, v203
	v_cvt_pk_bf16_f32 v64, v64, v65
	v_cvt_pk_bf16_f32 v65, v66, v67
	v_cvt_pk_bf16_f32 v66, v68, v69
	v_cvt_pk_bf16_f32 v67, v70, v71
	v_add_f32_e32 v203, v79, v203
	v_cvt_pk_bf16_f32 v68, v72, v73
	v_cvt_pk_bf16_f32 v69, v74, v75
	v_cvt_pk_bf16_f32 v70, v76, v77
	v_cvt_pk_bf16_f32 v71, v78, v79
	ds_read_b128 v[72:75], v205 offset:26720
	ds_read_b128 v[76:79], v207 offset:26720
	s_waitcnt lgkmcnt(5)
	v_mfma_f32_32x32x16_bf16 v[0:15], v[64:67], v[216:219], v[0:15]
	ds_read_b128 v[216:219], v205 offset:35936
	s_add_i32 s4, s4, 64
	s_mov_b64 s[0:1], 0x2000
	v_fmac_f32_e32 v203, v209, v208
	s_waitcnt lgkmcnt(5)
	v_mfma_f32_32x32x16_bf16 v[16:31], v[64:67], v[238:241], v[16:31]
	ds_read_b128 v[238:241], v205 offset:40544
	v_lshl_add_u64 v[176:177], v[176:177], 0, s[68:69]
	v_lshl_add_u64 v[178:179], v[178:179], 0, s[68:69]
	s_waitcnt lgkmcnt(5)
	v_mfma_f32_32x32x16_bf16 v[32:47], v[64:67], v[242:245], v[32:47]
	v_lshl_add_u64 v[180:181], v[180:181], 0, s[0:1]
	v_lshl_add_u64 v[182:183], v[182:183], 0, s[58:59]
	s_waitcnt lgkmcnt(4)
	v_mfma_f32_32x32x16_bf16 v[48:63], v[64:67], v[246:249], v[48:63]
	v_lshl_add_u64 v[184:185], v[184:185], 0, s[58:59]
	s_cmp_eq_u32 s16, s4
	s_waitcnt lgkmcnt(3)
	v_mfma_f32_32x32x16_bf16 v[0:15], v[68:71], v[72:75], v[0:15]
	s_waitcnt lgkmcnt(2)
	v_mfma_f32_32x32x16_bf16 v[16:31], v[68:71], v[76:79], v[16:31]
	s_waitcnt lgkmcnt(0)
	s_barrier
	v_mfma_f32_32x32x16_bf16 v[32:47], v[68:71], v[216:219], v[32:47]
	v_mfma_f32_32x32x16_bf16 v[48:63], v[68:71], v[238:241], v[48:63]
	s_cbranch_scc1 .LBB0_335
	s_mov_b32 s2, s17
	s_branch .LBB0_317
